# attention softmax half: cross-lane (permlane32) combines of row max and row sum moved out of the per-tile path (max only in the rescale path, sum once after the loop)
# speedup vs baseline: 1.0196x; 1.0109x over previous
; __device__ __forceinline__ void partialSM(f32x16& p0, f32x16& p1, float& m_reg, float& mn, float& alpha) {
;   constexpr float C = SCALE * 1.4426950408889634f;
;   float pmax = p0[0]; for (int r = 1; r < 16; ++r) pmax = fmaxf(pmax, p0[r]); for (int r = 0; r < 16; ++r) pmax = fmaxf(pmax, p1[r]);
;   { auto rr = __builtin_amdgcn_permlane32_swap(__float_as_uint(pmax), __float_as_uint(pmax), false, false);
;     pmax = fmaxf(__uint_as_float(rr[0]), __uint_as_float(rr[1])); }
;   if (__builtin_expect(__all(pmax - m_reg <= THR / SCALE), 1)) { mn = m_reg; alpha = 1.f; }
;   else { mn = fmaxf(m_reg, pmax); alpha = __builtin_amdgcn_exp2f((m_reg - mn) * C); m_reg = mn; }
;   float mnC = -mn * C + 5.f;
;   for (int r = 0; r < 16; ++r) p0[r] = fmaf(p0[r], C, mnC); for (int r = 0; r < 16; ++r) p1[r] = fmaf(p1[r], C, mnC);
;   for (int r = 0; r < 16; ++r) p0[r] = __builtin_amdgcn_exp2f(p0[r]);
; }
; __device__ __forceinline__ void finishSM(f32x16& p0, f32x16& p1, float alpha, float& l_reg, i32x8& pa) {
;   for (int r = 0; r < 16; ++r) p1[r] = __builtin_amdgcn_exp2f(p1[r]);
;   float ps = 0; for (int r = 0; r < 16; ++r) ps += p0[r]; for (int r = 0; r < 16; ++r) ps += p1[r];
;   { auto rr = __builtin_amdgcn_permlane32_swap(__float_as_uint(ps), __float_as_uint(ps), false, false);
;     ps = __uint_as_float(rr[0]) + __uint_as_float(rr[1]); }
;   l_reg = l_reg * alpha + ps;
; #pragma unroll
;   for (int i = 0; i < 4; ++i) { int w0 = 0, w1 = 0;
;     w0 = __builtin_amdgcn_cvt_pk_fp8_f32(p0[4 * i], p0[4 * i + 1], w0, false); w0 = __builtin_amdgcn_cvt_pk_fp8_f32(p0[4 * i + 2], p0[4 * i + 3], w0, true);
;     w1 = __builtin_amdgcn_cvt_pk_fp8_f32(p1[4 * i], p1[4 * i + 1], w1, false); w1 = __builtin_amdgcn_cvt_pk_fp8_f32(p1[4 * i + 2], p1[4 * i + 3], w1, true);
;     pa[i] = w0; pa[4 + i] = w1; }
; }
.Latt_m_nobar_0:
	v_max3_f32 v228, v64, v65, v66
	v_max3_f32 v229, v80, v81, v82
	v_max3_f32 v228, v228, v67, v68
	v_max3_f32 v229, v229, v83, v84
	v_max3_f32 v228, v228, v69, v70
	v_max3_f32 v229, v229, v85, v86
	v_max3_f32 v228, v228, v71, v72
	v_max3_f32 v229, v229, v87, v88
	v_max3_f32 v228, v228, v73, v74
	v_max3_f32 v229, v229, v89, v90
	v_max3_f32 v228, v228, v75, v76
	v_max3_f32 v229, v229, v91, v92
	v_max3_f32 v228, v228, v77, v78
	v_max3_f32 v229, v229, v93, v94
	v_max3_f32 v228, v228, v79, v95
	v_max_f32_e32 v228, v228, v229
	s_mov_b32 s5, 0
	v_cmp_ge_f32_e32 vcc, s13, v228
	v_mov_b32_e32 v226, 1.0
	s_cmp_eq_u32 s6, 0
	s_cbranch_scc1 .Latt_rare
	s_cmp_eq_u64 vcc, exec
	s_cbranch_scc0 .Latt_rare
.Latt_rare_back_0:
	v_exp_f32_e32 v64, v64
	v_exp_f32_e32 v65, v65
	v_exp_f32_e32 v66, v66
	v_exp_f32_e32 v67, v67
	v_add_f32_e32 v230, v64, v65
	v_exp_f32_e32 v68, v68
	v_add_f32_e32 v230, v66, v230
	v_exp_f32_e32 v69, v69
	v_cvt_pk_fp8_f32 v120, v64, v65
	v_add_f32_e32 v230, v67, v230
	v_exp_f32_e32 v70, v70
	v_add_f32_e32 v230, v68, v230
	v_exp_f32_e32 v71, v71
	v_cvt_pk_fp8_f32 v120, v66, v67 op_sel:[0,0,1]
	v_add_f32_e32 v230, v69, v230
	v_exp_f32_e32 v72, v72
	v_add_f32_e32 v230, v70, v230
	v_exp_f32_e32 v73, v73
	v_cvt_pk_fp8_f32 v121, v68, v69
	v_add_f32_e32 v230, v71, v230
	v_exp_f32_e32 v74, v74
	v_add_f32_e32 v230, v72, v230
	v_exp_f32_e32 v75, v75
	v_cvt_pk_fp8_f32 v121, v70, v71 op_sel:[0,0,1]
	v_add_f32_e32 v230, v73, v230
	v_exp_f32_e32 v76, v76
	v_add_f32_e32 v230, v74, v230
	v_exp_f32_e32 v77, v77
	v_cvt_pk_fp8_f32 v122, v72, v73
	v_add_f32_e32 v230, v75, v230
	v_exp_f32_e32 v78, v78
	v_add_f32_e32 v230, v76, v230
	v_exp_f32_e32 v79, v79
	v_cvt_pk_fp8_f32 v122, v74, v75 op_sel:[0,0,1]
	v_add_f32_e32 v230, v77, v230
	v_exp_f32_e32 v80, v80
	v_add_f32_e32 v230, v78, v230
	v_exp_f32_e32 v81, v81
	v_cvt_pk_fp8_f32 v123, v76, v77
	v_add_f32_e32 v230, v79, v230
	v_exp_f32_e32 v82, v82
	v_add_f32_e32 v230, v80, v230
	v_exp_f32_e32 v83, v83
	v_cvt_pk_fp8_f32 v123, v78, v79 op_sel:[0,0,1]
	v_add_f32_e32 v230, v81, v230
	v_exp_f32_e32 v84, v84
	v_add_f32_e32 v230, v82, v230
	v_exp_f32_e32 v85, v85
	v_cvt_pk_fp8_f32 v124, v80, v81
	v_add_f32_e32 v230, v83, v230
	v_exp_f32_e32 v86, v86
	v_add_f32_e32 v230, v84, v230
	v_exp_f32_e32 v87, v87
	v_cvt_pk_fp8_f32 v124, v82, v83 op_sel:[0,0,1]
	v_add_f32_e32 v230, v85, v230
	v_exp_f32_e32 v88, v88
	v_add_f32_e32 v230, v86, v230
	v_exp_f32_e32 v89, v89
	v_cvt_pk_fp8_f32 v125, v84, v85
	v_add_f32_e32 v230, v87, v230
	v_exp_f32_e32 v90, v90
	v_add_f32_e32 v230, v88, v230
	v_exp_f32_e32 v91, v91
	v_cvt_pk_fp8_f32 v125, v86, v87 op_sel:[0,0,1]
	v_add_f32_e32 v230, v89, v230
	v_exp_f32_e32 v92, v92
	v_add_f32_e32 v230, v90, v230
	v_exp_f32_e32 v93, v93
	v_cvt_pk_fp8_f32 v126, v88, v89
	v_add_f32_e32 v230, v91, v230
	v_exp_f32_e32 v94, v94
	v_add_f32_e32 v230, v92, v230
	v_exp_f32_e32 v95, v95
	v_cvt_pk_fp8_f32 v126, v90, v91 op_sel:[0,0,1]
	v_add_f32_e32 v230, v93, v230
	v_add_f32_e32 v230, v94, v230
	v_cvt_pk_fp8_f32 v127, v92, v93
	v_add_f32_e32 v230, v95, v230
	v_cvt_pk_fp8_f32 v127, v94, v95 op_sel:[0,0,1]
	v_fma_f32 v194, v194, v226, v230
	s_waitcnt lgkmcnt(0)
	s_cmp_eq_u32 s7, 0
	s_cbranch_scc0 .Latt_v_nobar_0
	s_barrier

; __device__ __forceinline__ void partialSM(f32x16& p0, f32x16& p1, float& m_reg, float& mn, float& alpha) {
;   constexpr float C = SCALE * 1.4426950408889634f;
;   float pmax = p0[0]; for (int r = 1; r < 16; ++r) pmax = fmaxf(pmax, p0[r]); for (int r = 0; r < 16; ++r) pmax = fmaxf(pmax, p1[r]);
;   { auto rr = __builtin_amdgcn_permlane32_swap(__float_as_uint(pmax), __float_as_uint(pmax), false, false);
;     pmax = fmaxf(__uint_as_float(rr[0]), __uint_as_float(rr[1])); }
;   if (__builtin_expect(__all(pmax - m_reg <= THR / SCALE), 1)) { mn = m_reg; alpha = 1.f; }
;   else { mn = fmaxf(m_reg, pmax); alpha = __builtin_amdgcn_exp2f((m_reg - mn) * C); m_reg = mn; }
.Latt_m_nobar_1:
	v_max3_f32 v228, v64, v65, v66
	v_max3_f32 v229, v80, v81, v82
	v_max3_f32 v228, v228, v67, v68
	v_max3_f32 v229, v229, v83, v84
	v_max3_f32 v228, v228, v69, v70
	v_max3_f32 v229, v229, v85, v86
	v_max3_f32 v228, v228, v71, v72
	v_max3_f32 v229, v229, v87, v88
	v_max3_f32 v228, v228, v73, v74
	v_max3_f32 v229, v229, v89, v90
	v_max3_f32 v228, v228, v75, v76
	v_max3_f32 v229, v229, v91, v92
	v_max3_f32 v228, v228, v77, v78
	v_max3_f32 v229, v229, v93, v94
	v_max3_f32 v228, v228, v79, v95
	v_max_f32_e32 v228, v228, v229
	s_mov_b32 s5, 1
	v_cmp_ge_f32_e32 vcc, s13, v228
	v_mov_b32_e32 v226, 1.0
	s_cmp_eq_u64 vcc, exec
	s_cbranch_scc0 .Latt_rare

; __device__ __forceinline__ void partialSM(f32x16& p0, f32x16& p1, float& m_reg, float& mn, float& alpha) {
;   constexpr float C = SCALE * 1.4426950408889634f;
;   float pmax = p0[0]; for (int r = 1; r < 16; ++r) pmax = fmaxf(pmax, p0[r]); for (int r = 0; r < 16; ++r) pmax = fmaxf(pmax, p1[r]);
;   { auto rr = __builtin_amdgcn_permlane32_swap(__float_as_uint(pmax), __float_as_uint(pmax), false, false);
;     pmax = fmaxf(__uint_as_float(rr[0]), __uint_as_float(rr[1])); }
;   if (__builtin_expect(__all(pmax - m_reg <= THR / SCALE), 1)) { mn = m_reg; alpha = 1.f; }
;   else { mn = fmaxf(m_reg, pmax); alpha = __builtin_amdgcn_exp2f((m_reg - mn) * C); m_reg = mn; }
.Latt_m_nobar_2:
	v_max3_f32 v228, v64, v65, v66
	v_max3_f32 v229, v80, v81, v82
	v_max3_f32 v228, v228, v67, v68
	v_max3_f32 v229, v229, v83, v84
	v_max3_f32 v228, v228, v69, v70
	v_max3_f32 v229, v229, v85, v86
	v_max3_f32 v228, v228, v71, v72
	v_max3_f32 v229, v229, v87, v88
	v_max3_f32 v228, v228, v73, v74
	v_max3_f32 v229, v229, v89, v90
	v_max3_f32 v228, v228, v75, v76
	v_max3_f32 v229, v229, v91, v92
	v_max3_f32 v228, v228, v77, v78
	v_max3_f32 v229, v229, v93, v94
	v_max3_f32 v228, v228, v79, v95
	v_max_f32_e32 v228, v228, v229
	s_mov_b32 s5, 2
	v_cmp_ge_f32_e32 vcc, s13, v228
	v_mov_b32_e32 v226, 1.0
	s_cmp_eq_u64 vcc, exec
	s_cbranch_scc0 .Latt_rare

; __device__ __forceinline__ void partialSM(f32x16& p0, f32x16& p1, float& m_reg, float& mn, float& alpha) {
;   constexpr float C = SCALE * 1.4426950408889634f;
;   float pmax = p0[0]; for (int r = 1; r < 16; ++r) pmax = fmaxf(pmax, p0[r]); for (int r = 0; r < 16; ++r) pmax = fmaxf(pmax, p1[r]);
;   { auto rr = __builtin_amdgcn_permlane32_swap(__float_as_uint(pmax), __float_as_uint(pmax), false, false);
;     pmax = fmaxf(__uint_as_float(rr[0]), __uint_as_float(rr[1])); }
;   if (__builtin_expect(__all(pmax - m_reg <= THR / SCALE), 1)) { mn = m_reg; alpha = 1.f; }
;   else { mn = fmaxf(m_reg, pmax); alpha = __builtin_amdgcn_exp2f((m_reg - mn) * C); m_reg = mn; }
.Latt_m_nobar_3:
	v_max3_f32 v228, v64, v65, v66
	v_max3_f32 v229, v80, v81, v82
	v_max3_f32 v228, v228, v67, v68
	v_max3_f32 v229, v229, v83, v84
	v_max3_f32 v228, v228, v69, v70
	v_max3_f32 v229, v229, v85, v86
	v_max3_f32 v228, v228, v71, v72
	v_max3_f32 v229, v229, v87, v88
	v_max3_f32 v228, v228, v73, v74
	v_max3_f32 v229, v229, v89, v90
	v_max3_f32 v228, v228, v75, v76
	v_max3_f32 v229, v229, v91, v92
	v_max3_f32 v228, v228, v77, v78
	v_max3_f32 v229, v229, v93, v94
	v_max3_f32 v228, v228, v79, v95
	v_max_f32_e32 v228, v228, v229
	s_mov_b32 s5, 3
	v_cmp_ge_f32_e32 vcc, s13, v228
	v_mov_b32_e32 v226, 1.0
	s_cmp_eq_u64 vcc, exec
	s_cbranch_scc0 .Latt_rare

; __device__ __forceinline__ bf16_t f2bf(float f) { return (bf16_t)(cvt_pk_bf16(f, 0.f) & 0xffffu); }
; #define SBAR() __builtin_amdgcn_sched_barrier(0)
; __device__ __forceinline__ int crow(int r, int hi) { return (r & 3) + 8 * (r >> 2) + 4 * hi; }
; __device__ __forceinline__ void finishSM(f32x16& p0, f32x16& p1, float alpha, float& l_reg, i32x8& pa) {
;     ...
;   { auto rr = __builtin_amdgcn_permlane32_swap(__float_as_uint(ps), __float_as_uint(ps), false, false);
;     ps = __uint_as_float(rr[0]) + __uint_as_float(rr[1]); }
;   l_reg = l_reg * alpha + ps;
; __device__ __forceinline__ void attn_body(const unsigned char* __restrict__ Qb, const unsigned char* __restrict__ Kh, const unsigned char* __restrict__ Vt,
;                                           bf16_t* __restrict__ Ob, int seq, char* lds) {
;     ...
;   STEP(NT - 1, pB0, pB1, mnB, alB, pA0, pA1, alA);
;   finishSM(pB0, pB1, alB, l_reg, pa); SBAR();
;   pv_d0(o, V_lds + sP * SHM_V, pa, r32, hi);
;     ...
;   if (hi == 0) li_l[r32] = l_reg; asm volatile("s_waitcnt lgkmcnt(0)" ::: "memory");
;   float rli[16];
; #pragma unroll
;   for (int r = 0; r < 16; ++r) rli[r] = 32.f * __builtin_amdgcn_rcpf(li_l[crow(r, hi)]);
;   bf16_t* Ow = Ob + (long)(wid * QBLK) * LDO;
; #pragma unroll
;   for (int r = 0; r < 16; ++r) { int orow = crow(r, hi);
;     for (int d0 = 0; d0 < 4; ++d0) Ow[(long)orow * LDO + d0 * 32 + r32] = f2bf(o[d0][r] * rli[r]); }
.Latt_tail:
	ds_read_b128 v[176:179], v221 offset:30720
	ds_read_b128 v[180:183], v221 offset:30736
	ds_read_b128 v[184:187], v221 offset:33280
	ds_read_b128 v[188:191], v221 offset:33296
	s_waitcnt lgkmcnt(2)
	v_mfma_scale_f32_32x32x64_f8f6f4 v[0:15], v[120:127], v[176:183], v[0:15], v237, v235 op_sel_hi:[0,0,0]
	ds_read_b128 v[176:179], v221 offset:35840
	ds_read_b128 v[180:183], v221 offset:35856
	s_waitcnt lgkmcnt(2)
	v_mfma_scale_f32_32x32x64_f8f6f4 v[16:31], v[120:127], v[184:191], v[16:31], v237, v235 op_sel_hi:[0,0,0]
	ds_read_b128 v[184:187], v221 offset:38400
	ds_read_b128 v[188:191], v221 offset:38416
	s_waitcnt lgkmcnt(2)
	v_mfma_scale_f32_32x32x64_f8f6f4 v[32:47], v[120:127], v[176:183], v[32:47], v237, v235 op_sel_hi:[0,0,0]
	s_waitcnt lgkmcnt(0)
	v_mfma_scale_f32_32x32x64_f8f6f4 v[48:63], v[120:127], v[184:191], v[48:63], v237, v235 op_sel_hi:[0,0,0]
	v_mov_b32_e32 v229, v194
	s_nop 1
	v_permlane32_swap_b32_e32 v194, v229
	v_add_f32_e32 v194, v194, v229
	s_mov_b32 exec_hi, 0
	ds_write_b32 v222, v194
	s_mov_b64 exec, -1
	s_waitcnt lgkmcnt(0)
	ds_read_b128 v[64:67], v223 offset:0
	ds_read_b128 v[68:71], v223 offset:32
	ds_read_b128 v[72:75], v223 offset:64
	ds_read_b128 v[76:79], v223 offset:96
	v_lshrrev_b32_e32 v231, 6, v192
	v_bfe_u32 v229, v192, 5, 1
	v_lshl_add_u32 v231, v231, 3, v229
	v_and_b32_e32 v201, 31, v192
	v_lshlrev_b32_e32 v231, 14, v231
	v_lshl_add_u32 v225, v201, 1, v231
	s_waitcnt lgkmcnt(0)
	v_rcp_f32_e32 v64, v64
	v_rcp_f32_e32 v65, v65
	v_rcp_f32_e32 v66, v66
	v_rcp_f32_e32 v67, v67
	v_rcp_f32_e32 v68, v68
	v_rcp_f32_e32 v69, v69
	v_rcp_f32_e32 v70, v70
	v_rcp_f32_e32 v71, v71
	v_rcp_f32_e32 v72, v72
	v_rcp_f32_e32 v73, v73
	v_rcp_f32_e32 v74, v74
	v_rcp_f32_e32 v75, v75
	v_rcp_f32_e32 v76, v76
	v_rcp_f32_e32 v77, v77
	v_rcp_f32_e32 v78, v78
	v_rcp_f32_e32 v79, v79
	s_nop 0
	v_mul_f32_e32 v64, 0x42000000, v64
	v_mul_f32_e32 v65, 0x42000000, v65
	v_mul_f32_e32 v66, 0x42000000, v66
	v_mul_f32_e32 v67, 0x42000000, v67
	v_mul_f32_e32 v68, 0x42000000, v68
	v_mul_f32_e32 v69, 0x42000000, v69
	v_mul_f32_e32 v70, 0x42000000, v70
	v_mul_f32_e32 v71, 0x42000000, v71
	v_mul_f32_e32 v72, 0x42000000, v72
	v_mul_f32_e32 v73, 0x42000000, v73
	v_mul_f32_e32 v74, 0x42000000, v74
	v_mul_f32_e32 v75, 0x42000000, v75
	v_mul_f32_e32 v76, 0x42000000, v76
	v_mul_f32_e32 v77, 0x42000000, v77
	v_mul_f32_e32 v78, 0x42000000, v78
	v_mul_f32_e32 v79, 0x42000000, v79
	s_nop 7
	v_mul_f32_e32 v80, v0, v64
	v_cvt_pk_bf16_f32 v80, v80, v195
	v_mul_f32_e32 v81, v16, v64
	v_cvt_pk_bf16_f32 v81, v81, v195
	v_mul_f32_e32 v82, v32, v64
	v_cvt_pk_bf16_f32 v82, v82, v195
	v_mul_f32_e32 v83, v48, v64
	v_cvt_pk_bf16_f32 v83, v83, v195
	global_store_short v225, v80, s[16:17] offset:0
	global_store_short v225, v81, s[16:17] offset:64
	global_store_short v225, v82, s[16:17] offset:128
	global_store_short v225, v83, s[16:17] offset:192
	v_add_u32_e32 v224, 0x1000, v225
	v_mul_f32_e32 v80, v1, v65
	v_cvt_pk_bf16_f32 v80, v80, v195
	v_mul_f32_e32 v81, v17, v65
	v_cvt_pk_bf16_f32 v81, v81, v195
	v_mul_f32_e32 v82, v33, v65
	v_cvt_pk_bf16_f32 v82, v82, v195
	v_mul_f32_e32 v83, v49, v65
	v_cvt_pk_bf16_f32 v83, v83, v195
	global_store_short v224, v80, s[16:17] offset:0
	global_store_short v224, v81, s[16:17] offset:64
	global_store_short v224, v82, s[16:17] offset:128
	global_store_short v224, v83, s[16:17] offset:192
	v_add_u32_e32 v224, 0x2000, v225
	v_mul_f32_e32 v80, v2, v66
	v_cvt_pk_bf16_f32 v80, v80, v195
	v_mul_f32_e32 v81, v18, v66
	v_cvt_pk_bf16_f32 v81, v81, v195
	v_mul_f32_e32 v82, v34, v66
	v_cvt_pk_bf16_f32 v82, v82, v195
	v_mul_f32_e32 v83, v50, v66
	v_cvt_pk_bf16_f32 v83, v83, v195
	global_store_short v224, v80, s[16:17] offset:0
	global_store_short v224, v81, s[16:17] offset:64
	global_store_short v224, v82, s[16:17] offset:128
	global_store_short v224, v83, s[16:17] offset:192
	v_add_u32_e32 v224, 0x3000, v225
	v_mul_f32_e32 v80, v3, v67
	v_cvt_pk_bf16_f32 v80, v80, v195
	v_mul_f32_e32 v81, v19, v67
	v_cvt_pk_bf16_f32 v81, v81, v195
	v_mul_f32_e32 v82, v35, v67
	v_cvt_pk_bf16_f32 v82, v82, v195
	v_mul_f32_e32 v83, v51, v67
	v_cvt_pk_bf16_f32 v83, v83, v195
	global_store_short v224, v80, s[16:17] offset:0
	global_store_short v224, v81, s[16:17] offset:64
	global_store_short v224, v82, s[16:17] offset:128
	global_store_short v224, v83, s[16:17] offset:192
	v_add_u32_e32 v224, 0x8000, v225
	v_mul_f32_e32 v80, v4, v68
	v_cvt_pk_bf16_f32 v80, v80, v195
	v_mul_f32_e32 v81, v20, v68
	v_cvt_pk_bf16_f32 v81, v81, v195
	v_mul_f32_e32 v82, v36, v68
	v_cvt_pk_bf16_f32 v82, v82, v195
	v_mul_f32_e32 v83, v52, v68
	v_cvt_pk_bf16_f32 v83, v83, v195
	global_store_short v224, v80, s[16:17] offset:0
	global_store_short v224, v81, s[16:17] offset:64
	global_store_short v224, v82, s[16:17] offset:128
	global_store_short v224, v83, s[16:17] offset:192
	v_add_u32_e32 v224, 0x9000, v225
	v_mul_f32_e32 v80, v5, v69
	v_cvt_pk_bf16_f32 v80, v80, v195
	v_mul_f32_e32 v81, v21, v69
	v_cvt_pk_bf16_f32 v81, v81, v195
	v_mul_f32_e32 v82, v37, v69
	v_cvt_pk_bf16_f32 v82, v82, v195
	v_mul_f32_e32 v83, v53, v69
	v_cvt_pk_bf16_f32 v83, v83, v195
	global_store_short v224, v80, s[16:17] offset:0
	global_store_short v224, v81, s[16:17] offset:64
	global_store_short v224, v82, s[16:17] offset:128
	global_store_short v224, v83, s[16:17] offset:192
	v_add_u32_e32 v224, 0xa000, v225
	v_mul_f32_e32 v80, v6, v70
	v_cvt_pk_bf16_f32 v80, v80, v195
	v_mul_f32_e32 v81, v22, v70
	v_cvt_pk_bf16_f32 v81, v81, v195
	v_mul_f32_e32 v82, v38, v70
	v_cvt_pk_bf16_f32 v82, v82, v195
	v_mul_f32_e32 v83, v54, v70
	v_cvt_pk_bf16_f32 v83, v83, v195
	global_store_short v224, v80, s[16:17] offset:0
; __device__ __forceinline__ bf16_t f2bf(float f) { return (bf16_t)(cvt_pk_bf16(f, 0.f) & 0xffffu); }
; __device__ __forceinline__ int crow(int r, int hi) { return (r & 3) + 8 * (r >> 2) + 4 * hi; }
; __device__ __forceinline__ void attn_body(const unsigned char* __restrict__ Qb, const unsigned char* __restrict__ Kh, const unsigned char* __restrict__ Vt,
;                                           bf16_t* __restrict__ Ob, int seq, char* lds) {
;     ...
;   for (int r = 0; r < 16; ++r) { int orow = crow(r, hi);
;     for (int d0 = 0; d0 < 4; ++d0) Ow[(long)orow * LDO + d0 * 32 + r32] = f2bf(o[d0][r] * rli[r]); }
;   asm volatile("s_waitcnt vmcnt(0)" ::: "memory");
;   __syncthreads();
; __global__ void __launch_bounds__(512) mega_fwd(Params p) {
;     ...
;             for (int it = bx; it < 256; it += G) { const int h = it & 7, qb = it >> 3;
;                 att::attn_body((const unsigned char*)B.Q + ((size_t)h * S_ + qb * 256) * 192, (const unsigned char*)B.K + (size_t)h * S_ * 192, (const unsigned char*)B.V + (size_t)h * 128 * S_,
;                                B.Y + (size_t)(qb * 256) * DM + 1024 + h * 128, S_, (char*)lds_raw); }
	global_store_short v224, v81, s[16:17] offset:64
	global_store_short v224, v82, s[16:17] offset:128
	global_store_short v224, v83, s[16:17] offset:192
	v_add_u32_e32 v224, 0xb000, v225
	v_mul_f32_e32 v80, v7, v71
	v_cvt_pk_bf16_f32 v80, v80, v195
	v_mul_f32_e32 v81, v23, v71
	v_cvt_pk_bf16_f32 v81, v81, v195
	v_mul_f32_e32 v82, v39, v71
	v_cvt_pk_bf16_f32 v82, v82, v195
	v_mul_f32_e32 v83, v55, v71
	v_cvt_pk_bf16_f32 v83, v83, v195
	global_store_short v224, v80, s[16:17] offset:0
	global_store_short v224, v81, s[16:17] offset:64
	global_store_short v224, v82, s[16:17] offset:128
	global_store_short v224, v83, s[16:17] offset:192
	v_add_u32_e32 v224, 0x10000, v225
	v_mul_f32_e32 v80, v8, v72
	v_cvt_pk_bf16_f32 v80, v80, v195
	v_mul_f32_e32 v81, v24, v72
	v_cvt_pk_bf16_f32 v81, v81, v195
	v_mul_f32_e32 v82, v40, v72
	v_cvt_pk_bf16_f32 v82, v82, v195
	v_mul_f32_e32 v83, v56, v72
	v_cvt_pk_bf16_f32 v83, v83, v195
	global_store_short v224, v80, s[16:17] offset:0
	global_store_short v224, v81, s[16:17] offset:64
	global_store_short v224, v82, s[16:17] offset:128
	global_store_short v224, v83, s[16:17] offset:192
	v_add_u32_e32 v224, 0x11000, v225
	v_mul_f32_e32 v80, v9, v73
	v_cvt_pk_bf16_f32 v80, v80, v195
	v_mul_f32_e32 v81, v25, v73
	v_cvt_pk_bf16_f32 v81, v81, v195
	v_mul_f32_e32 v82, v41, v73
	v_cvt_pk_bf16_f32 v82, v82, v195
	v_mul_f32_e32 v83, v57, v73
	v_cvt_pk_bf16_f32 v83, v83, v195
	global_store_short v224, v80, s[16:17] offset:0
	global_store_short v224, v81, s[16:17] offset:64
	global_store_short v224, v82, s[16:17] offset:128
	global_store_short v224, v83, s[16:17] offset:192
	v_add_u32_e32 v224, 0x12000, v225
	v_mul_f32_e32 v80, v10, v74
	v_cvt_pk_bf16_f32 v80, v80, v195
	v_mul_f32_e32 v81, v26, v74
	v_cvt_pk_bf16_f32 v81, v81, v195
	v_mul_f32_e32 v82, v42, v74
	v_cvt_pk_bf16_f32 v82, v82, v195
	v_mul_f32_e32 v83, v58, v74
	v_cvt_pk_bf16_f32 v83, v83, v195
	global_store_short v224, v80, s[16:17] offset:0
	global_store_short v224, v81, s[16:17] offset:64
	global_store_short v224, v82, s[16:17] offset:128
	global_store_short v224, v83, s[16:17] offset:192
	v_add_u32_e32 v224, 0x13000, v225
	v_mul_f32_e32 v80, v11, v75
	v_cvt_pk_bf16_f32 v80, v80, v195
	v_mul_f32_e32 v81, v27, v75
	v_cvt_pk_bf16_f32 v81, v81, v195
	v_mul_f32_e32 v82, v43, v75
	v_cvt_pk_bf16_f32 v82, v82, v195
	v_mul_f32_e32 v83, v59, v75
	v_cvt_pk_bf16_f32 v83, v83, v195
	global_store_short v224, v80, s[16:17] offset:0
	global_store_short v224, v81, s[16:17] offset:64
	global_store_short v224, v82, s[16:17] offset:128
	global_store_short v224, v83, s[16:17] offset:192
	v_add_u32_e32 v224, 0x18000, v225
	v_mul_f32_e32 v80, v12, v76
	v_cvt_pk_bf16_f32 v80, v80, v195
	v_mul_f32_e32 v81, v28, v76
	v_cvt_pk_bf16_f32 v81, v81, v195
	v_mul_f32_e32 v82, v44, v76
	v_cvt_pk_bf16_f32 v82, v82, v195
	v_mul_f32_e32 v83, v60, v76
	v_cvt_pk_bf16_f32 v83, v83, v195
	global_store_short v224, v80, s[16:17] offset:0
	global_store_short v224, v81, s[16:17] offset:64
	global_store_short v224, v82, s[16:17] offset:128
	global_store_short v224, v83, s[16:17] offset:192
	v_add_u32_e32 v224, 0x19000, v225
	v_mul_f32_e32 v80, v13, v77
	v_cvt_pk_bf16_f32 v80, v80, v195
	v_mul_f32_e32 v81, v29, v77
	v_cvt_pk_bf16_f32 v81, v81, v195
	v_mul_f32_e32 v82, v45, v77
	v_cvt_pk_bf16_f32 v82, v82, v195
	v_mul_f32_e32 v83, v61, v77
	v_cvt_pk_bf16_f32 v83, v83, v195
	global_store_short v224, v80, s[16:17] offset:0
	global_store_short v224, v81, s[16:17] offset:64
	global_store_short v224, v82, s[16:17] offset:128
	global_store_short v224, v83, s[16:17] offset:192
	v_add_u32_e32 v224, 0x1a000, v225
	v_mul_f32_e32 v80, v14, v78
	v_cvt_pk_bf16_f32 v80, v80, v195
	v_mul_f32_e32 v81, v30, v78
	v_cvt_pk_bf16_f32 v81, v81, v195
	v_mul_f32_e32 v82, v46, v78
	v_cvt_pk_bf16_f32 v82, v82, v195
	v_mul_f32_e32 v83, v62, v78
	v_cvt_pk_bf16_f32 v83, v83, v195
	global_store_short v224, v80, s[16:17] offset:0
	global_store_short v224, v81, s[16:17] offset:64
	global_store_short v224, v82, s[16:17] offset:128
	global_store_short v224, v83, s[16:17] offset:192
	v_add_u32_e32 v224, 0x1b000, v225
	v_mul_f32_e32 v80, v15, v79
	v_cvt_pk_bf16_f32 v80, v80, v195
	v_mul_f32_e32 v81, v31, v79
	v_cvt_pk_bf16_f32 v81, v81, v195
	v_mul_f32_e32 v82, v47, v79
	v_cvt_pk_bf16_f32 v82, v82, v195
	v_mul_f32_e32 v83, v63, v79
	v_cvt_pk_bf16_f32 v83, v83, v195
	global_store_short v224, v80, s[16:17] offset:0
	global_store_short v224, v81, s[16:17] offset:64
	global_store_short v224, v82, s[16:17] offset:128
	global_store_short v224, v83, s[16:17] offset:192
	s_waitcnt vmcnt(0)
	v_readlane_b32 s0, v252, 9
	s_nop 1
	s_add_i32 s25, s25, s0
	s_add_i32 s24, s24, s0
	s_cmpk_gt_i32 s25, 0xff
	s_waitcnt lgkmcnt(0)
	s_barrier
	v_readlane_b32 s1, v252, 10
	s_cbranch_scc1 .LBB0_297
	s_branch .LBB0_260
; __device__ __forceinline__ void partialSM(f32x16& p0, f32x16& p1, float& m_reg, float& mn, float& alpha) {
;     ...
;   { auto rr = __builtin_amdgcn_permlane32_swap(__float_as_uint(pmax), __float_as_uint(pmax), false, false);
;     pmax = fmaxf(__uint_as_float(rr[0]), __uint_as_float(rr[1])); }
;   if (__builtin_expect(__all(pmax - m_reg <= THR / SCALE), 1)) { mn = m_reg; alpha = 1.f; }
;   else { mn = fmaxf(m_reg, pmax); alpha = __builtin_amdgcn_exp2f((m_reg - mn) * C); m_reg = mn; }
.Latt_rare:
	v_mov_b32_e32 v229, v228
	s_nop 1
	v_permlane32_swap_b32_e32 v228, v229
	v_max_f32_e32 v228, v228, v229
	v_sub_f32_e32 v229, v228, v227
	v_max_f32_e32 v229, v193, v229
	v_sub_f32_e32 v231, v193, v229
	v_exp_f32_e32 v226, v231
	v_mov_b32_e32 v193, v229
	v_sub_f32_e32 v231, v236, v229
	v_sub_f32_e32 v229, v231, v227
	v_mov_b32_e32 v227, v231
	v_add_f32_e32 v64, v64, v229
	v_add_f32_e32 v65, v65, v229
	v_add_f32_e32 v66, v66, v229
	v_add_f32_e32 v67, v67, v229
	v_add_f32_e32 v68, v68, v229
	v_add_f32_e32 v69, v69, v229
	v_add_f32_e32 v70, v70, v229
	v_add_f32_e32 v71, v71, v229
	v_add_f32_e32 v72, v72, v229
	v_add_f32_e32 v73, v73, v229
	v_add_f32_e32 v74, v74, v229
	v_add_f32_e32 v75, v75, v229
	v_add_f32_e32 v76, v76, v229
	v_add_f32_e32 v77, v77, v229
	v_add_f32_e32 v78, v78, v229
	v_add_f32_e32 v79, v79, v229
	v_add_f32_e32 v80, v80, v229
	v_add_f32_e32 v81, v81, v229
	v_add_f32_e32 v82, v82, v229
	v_add_f32_e32 v83, v83, v229
	v_add_f32_e32 v84, v84, v229
	v_add_f32_e32 v85, v85, v229
	v_add_f32_e32 v86, v86, v229
	v_add_f32_e32 v87, v87, v229
	v_add_f32_e32 v88, v88, v229
	v_add_f32_e32 v89, v89, v229
	v_add_f32_e32 v90, v90, v229
	v_add_f32_e32 v91, v91, v229
	v_add_f32_e32 v92, v92, v229
	v_add_f32_e32 v93, v93, v229
	v_add_f32_e32 v94, v94, v229
	v_add_f32_e32 v95, v95, v229
	v_mov_b32_e32 v160, v227
	v_mov_b32_e32 v161, v227
	v_mov_b32_e32 v162, v227
	v_mov_b32_e32 v163, v227
	v_mov_b32_e32 v164, v227
	v_mov_b32_e32 v165, v227
	v_mov_b32_e32 v166, v227
	v_mov_b32_e32 v167, v227
	v_mov_b32_e32 v168, v227
	v_mov_b32_e32 v169, v227
	v_mov_b32_e32 v170, v227
	v_mov_b32_e32 v171, v227
	v_mov_b32_e32 v172, v227
	v_mov_b32_e32 v173, v227
	v_mov_b32_e32 v174, v227
	v_mov_b32_e32 v175, v227
	s_mov_b32 exec_hi, 0
	ds_write_b32 v222, v226 offset:128
	s_mov_b64 exec, -1
	s_waitcnt lgkmcnt(0)
	ds_read_b128 v[176:179], v223 offset:128
	ds_read_b128 v[180:183], v223 offset:160
	ds_read_b128 v[184:187], v223 offset:192
	ds_read_b128 v[188:191], v223 offset:224
	s_waitcnt lgkmcnt(0)
	v_mul_f32_e32 v0, v0, v176
	v_mul_f32_e32 v1, v1, v177
	v_mul_f32_e32 v2, v2, v178
	v_mul_f32_e32 v3, v3, v179
	v_mul_f32_e32 v4, v4, v180
	v_mul_f32_e32 v5, v5, v181
	v_mul_f32_e32 v6, v6, v182
	v_mul_f32_e32 v7, v7, v183
	v_mul_f32_e32 v8, v8, v184
	v_mul_f32_e32 v9, v9, v185
	v_mul_f32_e32 v10, v10, v186
	v_mul_f32_e32 v11, v11, v187
	v_mul_f32_e32 v12, v12, v188
	v_mul_f32_e32 v13, v13, v189
	v_mul_f32_e32 v14, v14, v190
	v_mul_f32_e32 v15, v15, v191
	v_mul_f32_e32 v16, v16, v176
	v_mul_f32_e32 v17, v17, v177
	v_mul_f32_e32 v18, v18, v178
	v_mul_f32_e32 v19, v19, v179
	v_mul_f32_e32 v20, v20, v180
	v_mul_f32_e32 v21, v21, v181
	v_mul_f32_e32 v22, v22, v182
	v_mul_f32_e32 v23, v23, v183
	v_mul_f32_e32 v24, v24, v184
	v_mul_f32_e32 v25, v25, v185
	v_mul_f32_e32 v26, v26, v186
	v_mul_f32_e32 v27, v27, v187
	v_mul_f32_e32 v28, v28, v188
	v_mul_f32_e32 v29, v29, v189
	v_mul_f32_e32 v30, v30, v190
	v_mul_f32_e32 v31, v31, v191
	v_mul_f32_e32 v32, v32, v176
	v_mul_f32_e32 v33, v33, v177
	v_mul_f32_e32 v34, v34, v178
	v_mul_f32_e32 v35, v35, v179
	v_mul_f32_e32 v36, v36, v180
	v_mul_f32_e32 v37, v37, v181
	v_mul_f32_e32 v38, v38, v182
	v_mul_f32_e32 v39, v39, v183
	v_mul_f32_e32 v40, v40, v184
	v_mul_f32_e32 v41, v41, v185
	v_mul_f32_e32 v42, v42, v186
	v_mul_f32_e32 v43, v43, v187
	v_mul_f32_e32 v44, v44, v188
	v_mul_f32_e32 v45, v45, v189
	v_mul_f32_e32 v46, v46, v190
	v_mul_f32_e32 v47, v47, v191
	v_mul_f32_e32 v48, v48, v176
	v_mul_f32_e32 v49, v49, v177
	v_mul_f32_e32 v50, v50, v178
	v_mul_f32_e32 v51, v51, v179
	v_mul_f32_e32 v52, v52, v180
	v_mul_f32_e32 v53, v53, v181
	v_mul_f32_e32 v54, v54, v182
	v_mul_f32_e32 v55, v55, v183
	v_mul_f32_e32 v56, v56, v184
	v_mul_f32_e32 v57, v57, v185
	v_mul_f32_e32 v58, v58, v186
	v_mul_f32_e32 v59, v59, v187
	v_mul_f32_e32 v60, v60, v188
	v_mul_f32_e32 v61, v61, v189
	v_mul_f32_e32 v62, v62, v190
	v_mul_f32_e32 v63, v63, v191
	s_cmp_eq_u32 s5, 0
	s_cbranch_scc1 .Latt_rare_back_0
	s_cmp_eq_u32 s5, 1
	s_cbranch_scc1 .Latt_rare_back_1
	s_cmp_eq_u32 s5, 2
	s_cbranch_scc1 .Latt_rare_back_2
	s_branch .Latt_rare_back_3
